# seams ph3->ph4 and ph4->next ph1 replaced by a barrier among the 32 workgroups sharing blockIdx%8 (row-local dependencies under the static tile order), agent-scope release/acquire kept
# baseline (speedup 1.0000x reference)
.LBB0_665:
	s_add_i32 s28, s8, 4
	s_cmp_lt_i32 s28, s45
	s_cselect_b64 s[20:21], -1, 0
	s_and_b64 s[12:13], s[12:13], s[20:21]
	s_andn2_b64 vcc, exec, s[12:13]
	s_cbranch_vccnz .LBB0_719
	s_cmp_lg_u32 s3, 0x100
	s_cbranch_scc1 .Lgb_orig_a
	s_waitcnt vmcnt(0) lgkmcnt(0)
	s_barrier
	v_readlane_b32 s98, v251, 20
	v_readlane_b32 s99, v251, 21
	s_nop 3
	s_mov_b64 exec, s[98:99]
	s_cbranch_execz .Lgb_done_a
	buffer_wbl2 sc1
	s_waitcnt vmcnt(0)
	v_readlane_b32 s98, v251, 2
	s_nop 3
	s_and_b32 s98, s98, 7
	s_lshl_b32 s98, s98, 8
	s_add_u32 s98, s98, 0x3800
	v_mov_b32_e32 v0, s98
	v_mov_b32_e32 v1, 1
	v_mov_b32_e32 v3, 0
	v_readlane_b32 s100, v254, 13
	s_nop 3
	s_lshl_b32 s100, s100, 1
	s_add_i32 s100, s100, 1
	s_lshl_b32 s100, s100, 5
	v_readlane_b32 s98, v251, 18
	v_readlane_b32 s99, v251, 19
	s_nop 7
	global_atomic_add v0, v1, s[98:99]
.Lgb_spin_a:
	global_load_dword v2, v0, s[98:99] sc1
	s_waitcnt vmcnt(0)
	v_readfirstlane_b32 s101, v2
	s_nop 3
	s_cmp_ge_u32 s101, s100
	s_cbranch_scc1 .Lgb_rel_a
	v_add_u32_e32 v3, 1, v3
	v_cmp_gt_u32_e32 vcc, 0x40000, v3
	s_cbranch_vccz .Lgb_rel_a
	s_sleep 1
	s_branch .Lgb_spin_a
.Lgb_rel_a:
	buffer_inv sc1
	s_waitcnt vmcnt(0)
.Lgb_done_a:
	s_mov_b64 exec, -1
	s_barrier
	s_branch .LBB0_719
.Lgb_orig_a:
	s_waitcnt vmcnt(0)
	s_waitcnt vmcnt(0) lgkmcnt(0)
	s_barrier
	s_mov_b64 s[12:13], exec
	v_readlane_b32 s30, v251, 20
	v_readlane_b32 s31, v251, 21
	s_and_b64 s[30:31], s[12:13], s[30:31]
	s_mov_b64 exec, s[30:31]
	s_cbranch_execz .LBB0_718
	v_readlane_b32 s6, v254, 2
	s_waitcnt vmcnt(0) expcnt(0) lgkmcnt(0)
	s_nop 0
	v_mov_b32_e32 v0, s6
	ds_read_b32 v2, v0
	v_readlane_b32 s6, v254, 3
	s_waitcnt lgkmcnt(0)
	v_cmp_ne_u32_e32 vcc, 0, v2
	v_mov_b32_e32 v0, s6
	ds_read_b32 v0, v0
	s_cbranch_vccnz .LBB0_682
	v_readlane_b32 s34, v251, 0
	v_readlane_b32 s35, v251, 1
	s_load_dwordx2 s[30:31], s[34:35], 0x4
	s_mov_b32 s41, 1
	s_waitcnt lgkmcnt(0)
	s_mul_i32 s40, s30, s3
	s_mul_i32 s40, s40, s31
	s_branch .LBB0_670

.LBB0_758:
	s_add_i32 s10, s8, 5
	s_cmp_ge_i32 s10, s45
	s_cbranch_scc1 .LBB0_206
	s_cmp_lg_u32 s3, 0x100
	s_cbranch_scc1 .Lgb_orig_b
	v_readlane_b32 s98, v254, 13
	s_nop 3
	s_cmp_ge_u32 s98, 3
	s_cbranch_scc1 .Lgb_orig_b
	s_waitcnt vmcnt(0) lgkmcnt(0)
	s_barrier
	v_readlane_b32 s98, v251, 20
	v_readlane_b32 s99, v251, 21
	s_nop 3
	s_mov_b64 exec, s[98:99]
	s_cbranch_execz .Lgb_done_b
	buffer_wbl2 sc1
	s_waitcnt vmcnt(0)
	v_readlane_b32 s98, v251, 2
	s_nop 3
	s_and_b32 s98, s98, 7
	s_lshl_b32 s98, s98, 8
	s_add_u32 s98, s98, 0x3800
	v_mov_b32_e32 v0, s98
	v_mov_b32_e32 v1, 1
	v_mov_b32_e32 v3, 0
	v_readlane_b32 s100, v254, 13
	s_nop 3
	s_lshl_b32 s100, s100, 1
	s_add_i32 s100, s100, 2
	s_lshl_b32 s100, s100, 5
	v_readlane_b32 s98, v251, 18
	v_readlane_b32 s99, v251, 19
	s_nop 7
	global_atomic_add v0, v1, s[98:99]

.Lgb_orig_b:
	s_waitcnt vmcnt(0)
	s_waitcnt vmcnt(0) lgkmcnt(0)
	s_barrier
	s_mov_b64 s[10:11], exec
	v_readlane_b32 s12, v251, 20
	v_readlane_b32 s13, v251, 21
	s_and_b64 s[12:13], s[10:11], s[12:13]
	s_mov_b64 exec, s[12:13]
	s_cbranch_execz .LBB0_205
	v_readlane_b32 s6, v254, 2
	s_waitcnt vmcnt(0) expcnt(0) lgkmcnt(0)
	s_nop 0
	v_mov_b32_e32 v0, s6
	ds_read_b32 v2, v0
	v_readlane_b32 s6, v254, 3
	s_waitcnt lgkmcnt(0)
	v_cmp_ne_u32_e32 vcc, 0, v2
	v_mov_b32_e32 v0, s6
	ds_read_b32 v0, v0
	s_cbranch_vccnz .LBB0_775
	v_readlane_b32 s16, v251, 0
	v_readlane_b32 s17, v251, 1
	s_load_dwordx2 s[12:13], s[16:17], 0x4
	s_mov_b32 s23, 1
	s_waitcnt lgkmcnt(0)
	s_mul_i32 s22, s12, s3
	s_mul_i32 s22, s22, s13
	s_branch .LBB0_763
